# v015 with the SwiGLU epilogue exponent-argument multiply and (1+e)*q fma done as packed f32 (v_pk_mul_f32 / v_pk_fma_f32 with broadcast scalar), 37 VALU per row group
# baseline (speedup 1.0000x reference)
; __device__ __forceinline__ unsigned cvt_pk_bf16(float lo, float hi) { const cvt_f32x2_t v = {lo, hi}; const cvt_bf16x2_t b = __builtin_convertvector(v, cvt_bf16x2_t); return __builtin_bit_cast(unsigned, b); }
; __device__ __forceinline__ float silu_mul(float g, float u) { return g * u * __builtin_amdgcn_rcpf(1.0f + __builtin_amdgcn_exp2f(g * -1.4426950408889634f)); }
; __device__ __forceinline__ float rstd_from_slots(const float* slots, int row, int fq) {
;     const f32x4 s4 = *(const f32x4*)(slots + (size_t)row * 16 + 4 * fq);
;     float s = (s4[0] + s4[1]) + (s4[2] + s4[3]);
;     s += __shfl_xor(s, 16); s += __shfl_xor(s, 32);
;     return __builtin_amdgcn_rsqf(s * (1.0f / 1024.0f) + RMS_EPS_F);
; }
;     __device__ __forceinline__ void operator()(const f32x4 (&acc)[2][2][4][2], const Unit& u, int wr, int wc, int fr, int fq) const {
;     ...
;             for (int m = 0; m < 4; ++m) { const int row = row0 + ai * HALF + m * 16;
;                 const float sc = rstd_from_slots(slots, row, fq);
;                 const f32x4 g0 = acc[ai][0][m][0] * sc, g1 = acc[ai][0][m][1] * sc, u0 = acc[ai][1][m][0] * sc, u1 = acc[ai][1][m][1] * sc;
;                 u32x4 w; w.x = cvt_pk_bf16(silu_mul(g0[0], u0[0]), silu_mul(g0[1], u0[1])); w.y = cvt_pk_bf16(silu_mul(g0[2], u0[2]), silu_mul(g0[3], u0[3]));
;                 w.z = cvt_pk_bf16(silu_mul(g1[0], u1[0]), silu_mul(g1[1], u1[1])); w.w = cvt_pk_bf16(silu_mul(g1[2], u1[2]), silu_mul(g1[3], u1[3]));
;                 __builtin_nontemporal_store(w, (u32x4*)(O + (size_t)row * ldc + col0)); }
.LBB0_675:
	v_xor_b32_e32 v216, 16, v161
	v_xor_b32_e32 v217, 32, v161
	v_lshlrev_b32_e32 v216, 2, v216
	v_lshlrev_b32_e32 v217, 2, v217
	s_waitcnt vmcnt(0)
	v_add_f32_e32 v172, v172, v173
	v_add_f32_e32 v173, v175, v174
	v_add_f32_e32 v176, v176, v177
	v_add_f32_e32 v177, v179, v178
	v_add_f32_e32 v180, v180, v181
	v_add_f32_e32 v181, v183, v182
	v_add_f32_e32 v184, v184, v185
	v_add_f32_e32 v185, v187, v186
	v_add_f32_e32 v188, v188, v189
	v_add_f32_e32 v189, v191, v190
	v_add_f32_e32 v192, v192, v193
	v_add_f32_e32 v193, v195, v194
	v_add_f32_e32 v196, v196, v197
	v_add_f32_e32 v197, v199, v198
	v_add_f32_e32 v200, v200, v201
	v_add_f32_e32 v201, v203, v202
	v_add_f32_e32 v172, v172, v173
	v_add_f32_e32 v176, v176, v177
	v_add_f32_e32 v180, v180, v181
	v_add_f32_e32 v184, v184, v185
	v_add_f32_e32 v188, v188, v189
	v_add_f32_e32 v192, v192, v193
	v_add_f32_e32 v196, v196, v197
	v_add_f32_e32 v200, v200, v201
	ds_bpermute_b32 v173, v216, v172
	ds_bpermute_b32 v177, v216, v176
	ds_bpermute_b32 v181, v216, v180
	ds_bpermute_b32 v185, v216, v184
	ds_bpermute_b32 v189, v216, v188
	ds_bpermute_b32 v193, v216, v192
	ds_bpermute_b32 v197, v216, v196
	ds_bpermute_b32 v201, v216, v200
	s_waitcnt lgkmcnt(0)
	v_add_f32_e32 v172, v172, v173
	v_add_f32_e32 v176, v176, v177
	v_add_f32_e32 v180, v180, v181
	v_add_f32_e32 v184, v184, v185
	v_add_f32_e32 v188, v188, v189
	v_add_f32_e32 v192, v192, v193
	v_add_f32_e32 v196, v196, v197
	v_add_f32_e32 v200, v200, v201
	ds_bpermute_b32 v173, v217, v172
	ds_bpermute_b32 v177, v217, v176
	ds_bpermute_b32 v181, v217, v180
	ds_bpermute_b32 v185, v217, v184
	ds_bpermute_b32 v189, v217, v188
	ds_bpermute_b32 v193, v217, v192
	ds_bpermute_b32 v197, v217, v196
	ds_bpermute_b32 v201, v217, v200
	s_waitcnt lgkmcnt(0)
	v_add_f32_e32 v172, v172, v173
	v_add_f32_e32 v176, v176, v177
	v_add_f32_e32 v180, v180, v181
	v_add_f32_e32 v184, v184, v185
	v_add_f32_e32 v188, v188, v189
	v_add_f32_e32 v192, v192, v193
	v_add_f32_e32 v196, v196, v197
	v_add_f32_e32 v200, v200, v201
	v_fmamk_f32 v174, v172, 0x3a800000, v162
	v_fmamk_f32 v178, v176, 0x3a800000, v162
	v_fmamk_f32 v182, v180, 0x3a800000, v162
	v_fmamk_f32 v186, v184, 0x3a800000, v162
	v_fmamk_f32 v190, v188, 0x3a800000, v162
	v_fmamk_f32 v194, v192, 0x3a800000, v162
	v_fmamk_f32 v198, v196, 0x3a800000, v162
	v_fmamk_f32 v202, v200, 0x3a800000, v162
	v_rsq_f32_e32 v172, v174
	v_rsq_f32_e32 v176, v178
	v_rsq_f32_e32 v180, v182
	v_rsq_f32_e32 v184, v186
	v_rsq_f32_e32 v188, v190
	v_rsq_f32_e32 v192, v194
	v_rsq_f32_e32 v196, v198
	v_rsq_f32_e32 v200, v202
	v_mul_f32_e32 v172, 0xbfb8aa3b, v172
	v_mul_f32_e32 v176, 0xbfb8aa3b, v176
	v_mul_f32_e32 v180, 0xbfb8aa3b, v180
	v_mul_f32_e32 v184, 0xbfb8aa3b, v184
	v_mul_f32_e32 v188, 0xbfb8aa3b, v188
	v_mul_f32_e32 v192, 0xbfb8aa3b, v192
	v_mul_f32_e32 v196, 0xbfb8aa3b, v196
	v_mul_f32_e32 v200, 0xbfb8aa3b, v200
	v_lshl_add_u32 v150, s0, 8, v152
	v_lshl_or_b32 v148, s1, 7, v157
	v_mov_b64_e32 v[146:147], s[10:11]
	v_ashrrev_i32_e32 v149, 31, v148
	v_lshlrev_b64 v[148:149], 1, v[148:149]
	s_andn2_b64 vcc, exec, s[2:3]
	v_mad_i64_i32 v[164:165], s[0:1], v150, s56, v[146:147]
	v_lshl_add_u64 v[164:165], v[164:165], 0, v[148:149]
	s_mov_b64 s[0:1], -1
	s_mov_b32 s98, 0x16000
	s_mov_b32 s99, 0
	v_pk_mul_f32 v[112:113], v[120:121], v[112:113]
	v_pk_mul_f32 v[114:115], v[122:123], v[114:115]
	v_pk_mul_f32 v[116:117], v[124:125], v[116:117]
	v_pk_mul_f32 v[118:119], v[126:127], v[118:119]
	v_pk_mul_f32 v[120:121], v[120:121], v[172:173] op_sel_hi:[1,0]
	v_pk_mul_f32 v[122:123], v[122:123], v[172:173] op_sel_hi:[1,0]
	v_pk_mul_f32 v[124:125], v[124:125], v[172:173] op_sel_hi:[1,0]
	v_pk_mul_f32 v[126:127], v[126:127], v[172:173] op_sel_hi:[1,0]
	v_exp_f32_e32 v120, v120
	v_exp_f32_e32 v121, v121
	v_exp_f32_e32 v122, v122
	v_exp_f32_e32 v123, v123
	v_exp_f32_e32 v124, v124
	v_exp_f32_e32 v125, v125
	v_exp_f32_e32 v126, v126
	v_exp_f32_e32 v127, v127
	v_pk_fma_f32 v[120:121], v[120:121], v[174:175], v[174:175] op_sel_hi:[1,0,0]
	v_pk_fma_f32 v[122:123], v[122:123], v[174:175], v[174:175] op_sel_hi:[1,0,0]
	v_pk_fma_f32 v[124:125], v[124:125], v[174:175], v[174:175] op_sel_hi:[1,0,0]
	v_pk_fma_f32 v[126:127], v[126:127], v[174:175], v[174:175] op_sel_hi:[1,0,0]
	v_rcp_f32_e32 v120, v120
	v_rcp_f32_e32 v121, v121
	v_rcp_f32_e32 v122, v122
	v_rcp_f32_e32 v123, v123
	v_rcp_f32_e32 v124, v124
	v_rcp_f32_e32 v125, v125
	v_rcp_f32_e32 v126, v126
	v_rcp_f32_e32 v127, v127
	v_pk_mul_f32 v[112:113], v[112:113], v[120:121]
	v_pk_mul_f32 v[114:115], v[114:115], v[122:123]
	v_pk_mul_f32 v[116:117], v[116:117], v[124:125]
	v_pk_mul_f32 v[118:119], v[118:119], v[126:127]
	v_cvt_pk_bf16_f32 v120, v116, v117
	v_cvt_pk_bf16_f32 v121, v118, v119
	v_cvt_pk_bf16_f32 v122, v112, v113
	v_cvt_pk_bf16_f32 v123, v114, v115
	global_store_dwordx4 v[164:165], v[120:123], off nt
	v_lshl_add_u64 v[166:167], v[164:165], 0, s[98:99]
	v_pk_mul_f32 v[96:97], v[104:105], v[96:97]
	v_pk_mul_f32 v[98:99], v[106:107], v[98:99]
	v_pk_mul_f32 v[100:101], v[108:109], v[100:101]
	v_pk_mul_f32 v[102:103], v[110:111], v[102:103]
	v_pk_mul_f32 v[104:105], v[104:105], v[176:177] op_sel_hi:[1,0]
	v_pk_mul_f32 v[106:107], v[106:107], v[176:177] op_sel_hi:[1,0]
	v_pk_mul_f32 v[108:109], v[108:109], v[176:177] op_sel_hi:[1,0]
	v_pk_mul_f32 v[110:111], v[110:111], v[176:177] op_sel_hi:[1,0]
	v_exp_f32_e32 v104, v104
	v_exp_f32_e32 v105, v105
	v_exp_f32_e32 v106, v106
	v_exp_f32_e32 v107, v107
	v_exp_f32_e32 v108, v108
	v_exp_f32_e32 v109, v109
	v_exp_f32_e32 v110, v110
	v_exp_f32_e32 v111, v111
	v_pk_fma_f32 v[104:105], v[104:105], v[178:179], v[178:179] op_sel_hi:[1,0,0]
; __device__ __forceinline__ unsigned cvt_pk_bf16(float lo, float hi) { const cvt_f32x2_t v = {lo, hi}; const cvt_bf16x2_t b = __builtin_convertvector(v, cvt_bf16x2_t); return __builtin_bit_cast(unsigned, b); }
; __device__ __forceinline__ float silu_mul(float g, float u) { return g * u * __builtin_amdgcn_rcpf(1.0f + __builtin_amdgcn_exp2f(g * -1.4426950408889634f)); }
;     __device__ __forceinline__ void operator()(const f32x4 (&acc)[2][2][4][2], const Unit& u, int wr, int wc, int fr, int fq) const {
;     ...
;             for (int m = 0; m < 4; ++m) { const int row = row0 + ai * HALF + m * 16;
;                 const float sc = rstd_from_slots(slots, row, fq);
;                 const f32x4 g0 = acc[ai][0][m][0] * sc, g1 = acc[ai][0][m][1] * sc, u0 = acc[ai][1][m][0] * sc, u1 = acc[ai][1][m][1] * sc;
;                 u32x4 w; w.x = cvt_pk_bf16(silu_mul(g0[0], u0[0]), silu_mul(g0[1], u0[1])); w.y = cvt_pk_bf16(silu_mul(g0[2], u0[2]), silu_mul(g0[3], u0[3]));
;                 w.z = cvt_pk_bf16(silu_mul(g1[0], u1[0]), silu_mul(g1[1], u1[1])); w.w = cvt_pk_bf16(silu_mul(g1[2], u1[2]), silu_mul(g1[3], u1[3]));
;                 __builtin_nontemporal_store(w, (u32x4*)(O + (size_t)row * ldc + col0)); }
	v_pk_fma_f32 v[106:107], v[106:107], v[178:179], v[178:179] op_sel_hi:[1,0,0]
	v_pk_fma_f32 v[108:109], v[108:109], v[178:179], v[178:179] op_sel_hi:[1,0,0]
	v_pk_fma_f32 v[110:111], v[110:111], v[178:179], v[178:179] op_sel_hi:[1,0,0]
	v_rcp_f32_e32 v104, v104
	v_rcp_f32_e32 v105, v105
	v_rcp_f32_e32 v106, v106
	v_rcp_f32_e32 v107, v107
	v_rcp_f32_e32 v108, v108
	v_rcp_f32_e32 v109, v109
	v_rcp_f32_e32 v110, v110
	v_rcp_f32_e32 v111, v111
	v_pk_mul_f32 v[96:97], v[96:97], v[104:105]
	v_pk_mul_f32 v[98:99], v[98:99], v[106:107]
	v_pk_mul_f32 v[100:101], v[100:101], v[108:109]
	v_pk_mul_f32 v[102:103], v[102:103], v[110:111]
	v_cvt_pk_bf16_f32 v104, v100, v101
	v_cvt_pk_bf16_f32 v105, v102, v103
	v_cvt_pk_bf16_f32 v106, v96, v97
	v_cvt_pk_bf16_f32 v107, v98, v99
	global_store_dwordx4 v[166:167], v[104:107], off nt
	v_lshl_add_u64 v[164:165], v[166:167], 0, s[98:99]
	v_pk_mul_f32 v[80:81], v[88:89], v[80:81]
	v_pk_mul_f32 v[82:83], v[90:91], v[82:83]
	v_pk_mul_f32 v[84:85], v[92:93], v[84:85]
	v_pk_mul_f32 v[86:87], v[94:95], v[86:87]
	v_pk_mul_f32 v[88:89], v[88:89], v[180:181] op_sel_hi:[1,0]
	v_pk_mul_f32 v[90:91], v[90:91], v[180:181] op_sel_hi:[1,0]
	v_pk_mul_f32 v[92:93], v[92:93], v[180:181] op_sel_hi:[1,0]
	v_pk_mul_f32 v[94:95], v[94:95], v[180:181] op_sel_hi:[1,0]
	v_exp_f32_e32 v88, v88
	v_exp_f32_e32 v89, v89
	v_exp_f32_e32 v90, v90
	v_exp_f32_e32 v91, v91
	v_exp_f32_e32 v92, v92
	v_exp_f32_e32 v93, v93
	v_exp_f32_e32 v94, v94
	v_exp_f32_e32 v95, v95
	v_pk_fma_f32 v[88:89], v[88:89], v[182:183], v[182:183] op_sel_hi:[1,0,0]
	v_pk_fma_f32 v[90:91], v[90:91], v[182:183], v[182:183] op_sel_hi:[1,0,0]
	v_pk_fma_f32 v[92:93], v[92:93], v[182:183], v[182:183] op_sel_hi:[1,0,0]
	v_pk_fma_f32 v[94:95], v[94:95], v[182:183], v[182:183] op_sel_hi:[1,0,0]
	v_rcp_f32_e32 v88, v88
	v_rcp_f32_e32 v89, v89
	v_rcp_f32_e32 v90, v90
	v_rcp_f32_e32 v91, v91
	v_rcp_f32_e32 v92, v92
	v_rcp_f32_e32 v93, v93
	v_rcp_f32_e32 v94, v94
	v_rcp_f32_e32 v95, v95
	v_pk_mul_f32 v[80:81], v[80:81], v[88:89]
	v_pk_mul_f32 v[82:83], v[82:83], v[90:91]
	v_pk_mul_f32 v[84:85], v[84:85], v[92:93]
	v_pk_mul_f32 v[86:87], v[86:87], v[94:95]
	v_cvt_pk_bf16_f32 v88, v84, v85
	v_cvt_pk_bf16_f32 v89, v86, v87
	v_cvt_pk_bf16_f32 v90, v80, v81
	v_cvt_pk_bf16_f32 v91, v82, v83
	global_store_dwordx4 v[164:165], v[88:91], off nt
	v_lshl_add_u64 v[166:167], v[164:165], 0, s[98:99]
	v_pk_mul_f32 v[64:65], v[72:73], v[64:65]
	v_pk_mul_f32 v[66:67], v[74:75], v[66:67]
	v_pk_mul_f32 v[68:69], v[76:77], v[68:69]
	v_pk_mul_f32 v[70:71], v[78:79], v[70:71]
	v_pk_mul_f32 v[72:73], v[72:73], v[184:185] op_sel_hi:[1,0]
	v_pk_mul_f32 v[74:75], v[74:75], v[184:185] op_sel_hi:[1,0]
	v_pk_mul_f32 v[76:77], v[76:77], v[184:185] op_sel_hi:[1,0]
	v_pk_mul_f32 v[78:79], v[78:79], v[184:185] op_sel_hi:[1,0]
	v_exp_f32_e32 v72, v72
	v_exp_f32_e32 v73, v73
	v_exp_f32_e32 v74, v74
	v_exp_f32_e32 v75, v75
	v_exp_f32_e32 v76, v76
	v_exp_f32_e32 v77, v77
	v_exp_f32_e32 v78, v78
	v_exp_f32_e32 v79, v79
	v_pk_fma_f32 v[72:73], v[72:73], v[186:187], v[186:187] op_sel_hi:[1,0,0]
	v_pk_fma_f32 v[74:75], v[74:75], v[186:187], v[186:187] op_sel_hi:[1,0,0]
	v_pk_fma_f32 v[76:77], v[76:77], v[186:187], v[186:187] op_sel_hi:[1,0,0]
	v_pk_fma_f32 v[78:79], v[78:79], v[186:187], v[186:187] op_sel_hi:[1,0,0]
	v_rcp_f32_e32 v72, v72
	v_rcp_f32_e32 v73, v73
	v_rcp_f32_e32 v74, v74
	v_rcp_f32_e32 v75, v75
	v_rcp_f32_e32 v76, v76
	v_rcp_f32_e32 v77, v77
	v_rcp_f32_e32 v78, v78
	v_rcp_f32_e32 v79, v79
	v_pk_mul_f32 v[64:65], v[64:65], v[72:73]
	v_pk_mul_f32 v[66:67], v[66:67], v[74:75]
	v_pk_mul_f32 v[68:69], v[68:69], v[76:77]
	v_pk_mul_f32 v[70:71], v[70:71], v[78:79]
	v_cvt_pk_bf16_f32 v72, v68, v69
	v_cvt_pk_bf16_f32 v73, v70, v71
	v_cvt_pk_bf16_f32 v74, v64, v65
	v_cvt_pk_bf16_f32 v75, v66, v67
	global_store_dwordx4 v[166:167], v[72:75], off nt
	s_mov_b32 s98, 0x6e000
	v_lshl_add_u64 v[164:165], v[166:167], 0, s[98:99]
	s_mov_b32 s98, 0x16000
	v_pk_mul_f32 v[48:49], v[56:57], v[48:49]
	v_pk_mul_f32 v[50:51], v[58:59], v[50:51]
	v_pk_mul_f32 v[52:53], v[60:61], v[52:53]
	v_pk_mul_f32 v[54:55], v[62:63], v[54:55]
	v_pk_mul_f32 v[56:57], v[56:57], v[188:189] op_sel_hi:[1,0]
	v_pk_mul_f32 v[58:59], v[58:59], v[188:189] op_sel_hi:[1,0]
	v_pk_mul_f32 v[60:61], v[60:61], v[188:189] op_sel_hi:[1,0]
	v_pk_mul_f32 v[62:63], v[62:63], v[188:189] op_sel_hi:[1,0]
	v_exp_f32_e32 v56, v56
	v_exp_f32_e32 v57, v57
	v_exp_f32_e32 v58, v58
	v_exp_f32_e32 v59, v59
	v_exp_f32_e32 v60, v60
	v_exp_f32_e32 v61, v61
	v_exp_f32_e32 v62, v62
	v_exp_f32_e32 v63, v63
	v_pk_fma_f32 v[56:57], v[56:57], v[190:191], v[190:191] op_sel_hi:[1,0,0]
	v_pk_fma_f32 v[58:59], v[58:59], v[190:191], v[190:191] op_sel_hi:[1,0,0]
	v_pk_fma_f32 v[60:61], v[60:61], v[190:191], v[190:191] op_sel_hi:[1,0,0]
	v_pk_fma_f32 v[62:63], v[62:63], v[190:191], v[190:191] op_sel_hi:[1,0,0]
	v_rcp_f32_e32 v56, v56
	v_rcp_f32_e32 v57, v57
	v_rcp_f32_e32 v58, v58
	v_rcp_f32_e32 v59, v59
	v_rcp_f32_e32 v60, v60
	v_rcp_f32_e32 v61, v61
; __device__ __forceinline__ unsigned cvt_pk_bf16(float lo, float hi) { const cvt_f32x2_t v = {lo, hi}; const cvt_bf16x2_t b = __builtin_convertvector(v, cvt_bf16x2_t); return __builtin_bit_cast(unsigned, b); }
; __device__ __forceinline__ float silu_mul(float g, float u) { return g * u * __builtin_amdgcn_rcpf(1.0f + __builtin_amdgcn_exp2f(g * -1.4426950408889634f)); }
;     __device__ __forceinline__ void operator()(const f32x4 (&acc)[2][2][4][2], const Unit& u, int wr, int wc, int fr, int fq) const {
;     ...
;             for (int m = 0; m < 4; ++m) { const int row = row0 + ai * HALF + m * 16;
;                 const float sc = rstd_from_slots(slots, row, fq);
;                 const f32x4 g0 = acc[ai][0][m][0] * sc, g1 = acc[ai][0][m][1] * sc, u0 = acc[ai][1][m][0] * sc, u1 = acc[ai][1][m][1] * sc;
;                 u32x4 w; w.x = cvt_pk_bf16(silu_mul(g0[0], u0[0]), silu_mul(g0[1], u0[1])); w.y = cvt_pk_bf16(silu_mul(g0[2], u0[2]), silu_mul(g0[3], u0[3]));
;                 w.z = cvt_pk_bf16(silu_mul(g1[0], u1[0]), silu_mul(g1[1], u1[1])); w.w = cvt_pk_bf16(silu_mul(g1[2], u1[2]), silu_mul(g1[3], u1[3]));
;                 __builtin_nontemporal_store(w, (u32x4*)(O + (size_t)row * ldc + col0)); }
	v_rcp_f32_e32 v62, v62
	v_rcp_f32_e32 v63, v63
	v_pk_mul_f32 v[48:49], v[48:49], v[56:57]
	v_pk_mul_f32 v[50:51], v[50:51], v[58:59]
	v_pk_mul_f32 v[52:53], v[52:53], v[60:61]
	v_pk_mul_f32 v[54:55], v[54:55], v[62:63]
	v_cvt_pk_bf16_f32 v56, v52, v53
	v_cvt_pk_bf16_f32 v57, v54, v55
	v_cvt_pk_bf16_f32 v58, v48, v49
	v_cvt_pk_bf16_f32 v59, v50, v51
	global_store_dwordx4 v[164:165], v[56:59], off nt
	v_lshl_add_u64 v[166:167], v[164:165], 0, s[98:99]
	v_pk_mul_f32 v[32:33], v[40:41], v[32:33]
	v_pk_mul_f32 v[34:35], v[42:43], v[34:35]
	v_pk_mul_f32 v[36:37], v[44:45], v[36:37]
	v_pk_mul_f32 v[38:39], v[46:47], v[38:39]
	v_pk_mul_f32 v[40:41], v[40:41], v[192:193] op_sel_hi:[1,0]
	v_pk_mul_f32 v[42:43], v[42:43], v[192:193] op_sel_hi:[1,0]
	v_pk_mul_f32 v[44:45], v[44:45], v[192:193] op_sel_hi:[1,0]
	v_pk_mul_f32 v[46:47], v[46:47], v[192:193] op_sel_hi:[1,0]
	v_exp_f32_e32 v40, v40
	v_exp_f32_e32 v41, v41
	v_exp_f32_e32 v42, v42
	v_exp_f32_e32 v43, v43
	v_exp_f32_e32 v44, v44
	v_exp_f32_e32 v45, v45
	v_exp_f32_e32 v46, v46
	v_exp_f32_e32 v47, v47
	v_pk_fma_f32 v[40:41], v[40:41], v[194:195], v[194:195] op_sel_hi:[1,0,0]
	v_pk_fma_f32 v[42:43], v[42:43], v[194:195], v[194:195] op_sel_hi:[1,0,0]
	v_pk_fma_f32 v[44:45], v[44:45], v[194:195], v[194:195] op_sel_hi:[1,0,0]
	v_pk_fma_f32 v[46:47], v[46:47], v[194:195], v[194:195] op_sel_hi:[1,0,0]
	v_rcp_f32_e32 v40, v40
	v_rcp_f32_e32 v41, v41
	v_rcp_f32_e32 v42, v42
	v_rcp_f32_e32 v43, v43
	v_rcp_f32_e32 v44, v44
	v_rcp_f32_e32 v45, v45
	v_rcp_f32_e32 v46, v46
	v_rcp_f32_e32 v47, v47
	v_pk_mul_f32 v[32:33], v[32:33], v[40:41]
	v_pk_mul_f32 v[34:35], v[34:35], v[42:43]
	v_pk_mul_f32 v[36:37], v[36:37], v[44:45]
	v_pk_mul_f32 v[38:39], v[38:39], v[46:47]
	v_cvt_pk_bf16_f32 v40, v36, v37
	v_cvt_pk_bf16_f32 v41, v38, v39
	v_cvt_pk_bf16_f32 v42, v32, v33
	v_cvt_pk_bf16_f32 v43, v34, v35
	global_store_dwordx4 v[166:167], v[40:43], off nt
	v_lshl_add_u64 v[164:165], v[166:167], 0, s[98:99]
	v_pk_mul_f32 v[16:17], v[24:25], v[16:17]
	v_pk_mul_f32 v[18:19], v[26:27], v[18:19]
	v_pk_mul_f32 v[20:21], v[28:29], v[20:21]
	v_pk_mul_f32 v[22:23], v[30:31], v[22:23]
	v_pk_mul_f32 v[24:25], v[24:25], v[196:197] op_sel_hi:[1,0]
	v_pk_mul_f32 v[26:27], v[26:27], v[196:197] op_sel_hi:[1,0]
	v_pk_mul_f32 v[28:29], v[28:29], v[196:197] op_sel_hi:[1,0]
	v_pk_mul_f32 v[30:31], v[30:31], v[196:197] op_sel_hi:[1,0]
	v_exp_f32_e32 v24, v24
	v_exp_f32_e32 v25, v25
	v_exp_f32_e32 v26, v26
	v_exp_f32_e32 v27, v27
	v_exp_f32_e32 v28, v28
	v_exp_f32_e32 v29, v29
	v_exp_f32_e32 v30, v30
	v_exp_f32_e32 v31, v31
	v_pk_fma_f32 v[24:25], v[24:25], v[198:199], v[198:199] op_sel_hi:[1,0,0]
	v_pk_fma_f32 v[26:27], v[26:27], v[198:199], v[198:199] op_sel_hi:[1,0,0]
	v_pk_fma_f32 v[28:29], v[28:29], v[198:199], v[198:199] op_sel_hi:[1,0,0]
	v_pk_fma_f32 v[30:31], v[30:31], v[198:199], v[198:199] op_sel_hi:[1,0,0]
	v_rcp_f32_e32 v24, v24
	v_rcp_f32_e32 v25, v25
	v_rcp_f32_e32 v26, v26
	v_rcp_f32_e32 v27, v27
	v_rcp_f32_e32 v28, v28
	v_rcp_f32_e32 v29, v29
	v_rcp_f32_e32 v30, v30
	v_rcp_f32_e32 v31, v31
	v_pk_mul_f32 v[16:17], v[16:17], v[24:25]
	v_pk_mul_f32 v[18:19], v[18:19], v[26:27]
	v_pk_mul_f32 v[20:21], v[20:21], v[28:29]
	v_pk_mul_f32 v[22:23], v[22:23], v[30:31]
	v_cvt_pk_bf16_f32 v24, v20, v21
	v_cvt_pk_bf16_f32 v25, v22, v23
	v_cvt_pk_bf16_f32 v26, v16, v17
	v_cvt_pk_bf16_f32 v27, v18, v19
	global_store_dwordx4 v[164:165], v[24:27], off nt
	v_lshl_add_u64 v[166:167], v[164:165], 0, s[98:99]
	v_pk_mul_f32 v[0:1], v[8:9], v[0:1]
	v_pk_mul_f32 v[2:3], v[10:11], v[2:3]
	v_pk_mul_f32 v[4:5], v[12:13], v[4:5]
	v_pk_mul_f32 v[6:7], v[14:15], v[6:7]
	v_pk_mul_f32 v[8:9], v[8:9], v[200:201] op_sel_hi:[1,0]
	v_pk_mul_f32 v[10:11], v[10:11], v[200:201] op_sel_hi:[1,0]
	v_pk_mul_f32 v[12:13], v[12:13], v[200:201] op_sel_hi:[1,0]
	v_pk_mul_f32 v[14:15], v[14:15], v[200:201] op_sel_hi:[1,0]
	v_exp_f32_e32 v8, v8
	v_exp_f32_e32 v9, v9
	v_exp_f32_e32 v10, v10
	v_exp_f32_e32 v11, v11
	v_exp_f32_e32 v12, v12
	v_exp_f32_e32 v13, v13
	v_exp_f32_e32 v14, v14
	v_exp_f32_e32 v15, v15
	v_pk_fma_f32 v[8:9], v[8:9], v[202:203], v[202:203] op_sel_hi:[1,0,0]
	v_pk_fma_f32 v[10:11], v[10:11], v[202:203], v[202:203] op_sel_hi:[1,0,0]
	v_pk_fma_f32 v[12:13], v[12:13], v[202:203], v[202:203] op_sel_hi:[1,0,0]
	v_pk_fma_f32 v[14:15], v[14:15], v[202:203], v[202:203] op_sel_hi:[1,0,0]
	v_rcp_f32_e32 v8, v8
	v_rcp_f32_e32 v9, v9
	v_rcp_f32_e32 v10, v10
	v_rcp_f32_e32 v11, v11
	v_rcp_f32_e32 v12, v12
	v_rcp_f32_e32 v13, v13
	v_rcp_f32_e32 v14, v14
	v_rcp_f32_e32 v15, v15
	v_pk_mul_f32 v[0:1], v[0:1], v[8:9]
	v_pk_mul_f32 v[2:3], v[2:3], v[10:11]
	v_pk_mul_f32 v[4:5], v[4:5], v[12:13]
	v_pk_mul_f32 v[6:7], v[6:7], v[14:15]
	v_cvt_pk_bf16_f32 v8, v4, v5
	v_cvt_pk_bf16_f32 v9, v6, v7
	v_cvt_pk_bf16_f32 v10, v0, v1
	v_cvt_pk_bf16_f32 v11, v2, v3
	global_store_dwordx4 v[166:167], v[8:11], off nt
	s_cbranch_vccnz .LBB0_668
	s_andn2_b64 vcc, exec, s[6:7]
	s_cbranch_vccnz .LBB0_667
	s_barrier
	s_branch .LBB0_667

; __device__ __forceinline__ unsigned cvt_pk_bf16(float lo, float hi) { const cvt_f32x2_t v = {lo, hi}; const cvt_bf16x2_t b = __builtin_convertvector(v, cvt_bf16x2_t); return __builtin_bit_cast(unsigned, b); }
; __device__ __forceinline__ float silu_mul(float g, float u) { return g * u * __builtin_amdgcn_rcpf(1.0f + __builtin_amdgcn_exp2f(g * -1.4426950408889634f)); }
; __device__ __forceinline__ float rstd_from_slots(const float* slots, int row, int fq) {
;     const f32x4 s4 = *(const f32x4*)(slots + (size_t)row * 16 + 4 * fq);
;     float s = (s4[0] + s4[1]) + (s4[2] + s4[3]);
;     s += __shfl_xor(s, 16); s += __shfl_xor(s, 32);
;     return __builtin_amdgcn_rsqf(s * (1.0f / 1024.0f) + RMS_EPS_F);
; }
;     __device__ __forceinline__ void operator()(const f32x4 (&acc)[2][2][4][2], const Unit& u, int wr, int wc, int fr, int fq) const {
;     ...
;             for (int m = 0; m < 4; ++m) { const int row = row0 + ai * HALF + m * 16;
;                 const float sc = rstd_from_slots(slots, row, fq);
;                 const f32x4 g0 = acc[ai][0][m][0] * sc, g1 = acc[ai][0][m][1] * sc, u0 = acc[ai][1][m][0] * sc, u1 = acc[ai][1][m][1] * sc;
;                 u32x4 w; w.x = cvt_pk_bf16(silu_mul(g0[0], u0[0]), silu_mul(g0[1], u0[1])); w.y = cvt_pk_bf16(silu_mul(g0[2], u0[2]), silu_mul(g0[3], u0[3]));
;                 w.z = cvt_pk_bf16(silu_mul(g1[0], u1[0]), silu_mul(g1[1], u1[1])); w.w = cvt_pk_bf16(silu_mul(g1[2], u1[2]), silu_mul(g1[3], u1[3]));
;                 __builtin_nontemporal_store(w, (u32x4*)(O + (size_t)row * ldc + col0)); }
.LBB0_1114:
	v_xor_b32_e32 v216, 16, v160
	v_xor_b32_e32 v217, 32, v160
	v_lshlrev_b32_e32 v216, 2, v216
	v_lshlrev_b32_e32 v217, 2, v217
	s_waitcnt vmcnt(0)
	v_add_f32_e32 v172, v172, v173
	v_add_f32_e32 v173, v175, v174
	v_add_f32_e32 v176, v176, v177
	v_add_f32_e32 v177, v179, v178
	v_add_f32_e32 v180, v180, v181
	v_add_f32_e32 v181, v183, v182
	v_add_f32_e32 v184, v184, v185
	v_add_f32_e32 v185, v187, v186
	v_add_f32_e32 v188, v188, v189
	v_add_f32_e32 v189, v191, v190
	v_add_f32_e32 v192, v192, v193
	v_add_f32_e32 v193, v195, v194
	v_add_f32_e32 v196, v196, v197
	v_add_f32_e32 v197, v199, v198
	v_add_f32_e32 v200, v200, v201
	v_add_f32_e32 v201, v203, v202
	v_add_f32_e32 v172, v172, v173
	v_add_f32_e32 v176, v176, v177
	v_add_f32_e32 v180, v180, v181
	v_add_f32_e32 v184, v184, v185
	v_add_f32_e32 v188, v188, v189
	v_add_f32_e32 v192, v192, v193
	v_add_f32_e32 v196, v196, v197
	v_add_f32_e32 v200, v200, v201
	ds_bpermute_b32 v173, v216, v172
	ds_bpermute_b32 v177, v216, v176
	ds_bpermute_b32 v181, v216, v180
	ds_bpermute_b32 v185, v216, v184
	ds_bpermute_b32 v189, v216, v188
	ds_bpermute_b32 v193, v216, v192
	ds_bpermute_b32 v197, v216, v196
	ds_bpermute_b32 v201, v216, v200
	s_waitcnt lgkmcnt(0)
	v_add_f32_e32 v172, v172, v173
	v_add_f32_e32 v176, v176, v177
	v_add_f32_e32 v180, v180, v181
	v_add_f32_e32 v184, v184, v185
	v_add_f32_e32 v188, v188, v189
	v_add_f32_e32 v192, v192, v193
	v_add_f32_e32 v196, v196, v197
	v_add_f32_e32 v200, v200, v201
	ds_bpermute_b32 v173, v217, v172
	ds_bpermute_b32 v177, v217, v176
	ds_bpermute_b32 v181, v217, v180
	ds_bpermute_b32 v185, v217, v184
	ds_bpermute_b32 v189, v217, v188
	ds_bpermute_b32 v193, v217, v192
	ds_bpermute_b32 v197, v217, v196
	ds_bpermute_b32 v201, v217, v200
	s_waitcnt lgkmcnt(0)
	v_add_f32_e32 v172, v172, v173
	v_add_f32_e32 v176, v176, v177
	v_add_f32_e32 v180, v180, v181
	v_add_f32_e32 v184, v184, v185
	v_add_f32_e32 v188, v188, v189
	v_add_f32_e32 v192, v192, v193
	v_add_f32_e32 v196, v196, v197
	v_add_f32_e32 v200, v200, v201
	v_fmamk_f32 v174, v172, 0x3a800000, v161
	v_fmamk_f32 v178, v176, 0x3a800000, v161
	v_fmamk_f32 v182, v180, 0x3a800000, v161
	v_fmamk_f32 v186, v184, 0x3a800000, v161
	v_fmamk_f32 v190, v188, 0x3a800000, v161
	v_fmamk_f32 v194, v192, 0x3a800000, v161
	v_fmamk_f32 v198, v196, 0x3a800000, v161
	v_fmamk_f32 v202, v200, 0x3a800000, v161
	v_rsq_f32_e32 v172, v174
	v_rsq_f32_e32 v176, v178
	v_rsq_f32_e32 v180, v182
	v_rsq_f32_e32 v184, v186
	v_rsq_f32_e32 v188, v190
	v_rsq_f32_e32 v192, v194
	v_rsq_f32_e32 v196, v198
	v_rsq_f32_e32 v200, v202
	v_mul_f32_e32 v172, 0xbfb8aa3b, v172
	v_mul_f32_e32 v176, 0xbfb8aa3b, v176
	v_mul_f32_e32 v180, 0xbfb8aa3b, v180
	v_mul_f32_e32 v184, 0xbfb8aa3b, v184
	v_mul_f32_e32 v188, 0xbfb8aa3b, v188
	v_mul_f32_e32 v192, 0xbfb8aa3b, v192
	v_mul_f32_e32 v196, 0xbfb8aa3b, v196
	v_mul_f32_e32 v200, 0xbfb8aa3b, v200
	v_lshl_add_u32 v150, s0, 8, v152
	v_lshl_or_b32 v148, s1, 7, v156
	v_mov_b64_e32 v[146:147], s[10:11]
	v_ashrrev_i32_e32 v149, 31, v148
	v_lshlrev_b64 v[148:149], 1, v[148:149]
	s_andn2_b64 vcc, exec, s[2:3]
	v_mad_i64_i32 v[164:165], s[0:1], v150, s56, v[146:147]
	v_lshl_add_u64 v[164:165], v[164:165], 0, v[148:149]
	s_mov_b64 s[0:1], -1
	s_mov_b32 s98, 0x16000
	s_mov_b32 s99, 0
	v_pk_mul_f32 v[112:113], v[120:121], v[112:113]
	v_pk_mul_f32 v[114:115], v[122:123], v[114:115]
	v_pk_mul_f32 v[116:117], v[124:125], v[116:117]
	v_pk_mul_f32 v[118:119], v[126:127], v[118:119]
	v_pk_mul_f32 v[120:121], v[120:121], v[172:173] op_sel_hi:[1,0]
	v_pk_mul_f32 v[122:123], v[122:123], v[172:173] op_sel_hi:[1,0]
	v_pk_mul_f32 v[124:125], v[124:125], v[172:173] op_sel_hi:[1,0]
	v_pk_mul_f32 v[126:127], v[126:127], v[172:173] op_sel_hi:[1,0]
	v_exp_f32_e32 v120, v120
	v_exp_f32_e32 v121, v121
	v_exp_f32_e32 v122, v122
	v_exp_f32_e32 v123, v123
	v_exp_f32_e32 v124, v124
	v_exp_f32_e32 v125, v125
	v_exp_f32_e32 v126, v126
	v_exp_f32_e32 v127, v127
	v_pk_fma_f32 v[120:121], v[120:121], v[174:175], v[174:175] op_sel_hi:[1,0,0]
	v_pk_fma_f32 v[122:123], v[122:123], v[174:175], v[174:175] op_sel_hi:[1,0,0]
	v_pk_fma_f32 v[124:125], v[124:125], v[174:175], v[174:175] op_sel_hi:[1,0,0]
	v_pk_fma_f32 v[126:127], v[126:127], v[174:175], v[174:175] op_sel_hi:[1,0,0]
	v_rcp_f32_e32 v120, v120
	v_rcp_f32_e32 v121, v121
	v_rcp_f32_e32 v122, v122
	v_rcp_f32_e32 v123, v123
	v_rcp_f32_e32 v124, v124
	v_rcp_f32_e32 v125, v125
	v_rcp_f32_e32 v126, v126
	v_rcp_f32_e32 v127, v127
	v_pk_mul_f32 v[112:113], v[112:113], v[120:121]
	v_pk_mul_f32 v[114:115], v[114:115], v[122:123]
	v_pk_mul_f32 v[116:117], v[116:117], v[124:125]
	v_pk_mul_f32 v[118:119], v[118:119], v[126:127]
	v_cvt_pk_bf16_f32 v120, v116, v117
	v_cvt_pk_bf16_f32 v121, v118, v119
	v_cvt_pk_bf16_f32 v122, v112, v113
	v_cvt_pk_bf16_f32 v123, v114, v115
	global_store_dwordx4 v[164:165], v[120:123], off nt
	v_lshl_add_u64 v[166:167], v[164:165], 0, s[98:99]
	v_pk_mul_f32 v[96:97], v[104:105], v[96:97]
	v_pk_mul_f32 v[98:99], v[106:107], v[98:99]
	v_pk_mul_f32 v[100:101], v[108:109], v[100:101]
	v_pk_mul_f32 v[102:103], v[110:111], v[102:103]
	v_pk_mul_f32 v[104:105], v[104:105], v[176:177] op_sel_hi:[1,0]
	v_pk_mul_f32 v[106:107], v[106:107], v[176:177] op_sel_hi:[1,0]
	v_pk_mul_f32 v[108:109], v[108:109], v[176:177] op_sel_hi:[1,0]
	v_pk_mul_f32 v[110:111], v[110:111], v[176:177] op_sel_hi:[1,0]
	v_exp_f32_e32 v104, v104
	v_exp_f32_e32 v105, v105
	v_exp_f32_e32 v106, v106
	v_exp_f32_e32 v107, v107
	v_exp_f32_e32 v108, v108
	v_exp_f32_e32 v109, v109
	v_exp_f32_e32 v110, v110
	v_exp_f32_e32 v111, v111
	v_pk_fma_f32 v[104:105], v[104:105], v[178:179], v[178:179] op_sel_hi:[1,0,0]
; __device__ __forceinline__ unsigned cvt_pk_bf16(float lo, float hi) { const cvt_f32x2_t v = {lo, hi}; const cvt_bf16x2_t b = __builtin_convertvector(v, cvt_bf16x2_t); return __builtin_bit_cast(unsigned, b); }
; __device__ __forceinline__ float silu_mul(float g, float u) { return g * u * __builtin_amdgcn_rcpf(1.0f + __builtin_amdgcn_exp2f(g * -1.4426950408889634f)); }
;     __device__ __forceinline__ void operator()(const f32x4 (&acc)[2][2][4][2], const Unit& u, int wr, int wc, int fr, int fq) const {
;     ...
;             for (int m = 0; m < 4; ++m) { const int row = row0 + ai * HALF + m * 16;
;                 const float sc = rstd_from_slots(slots, row, fq);
;                 const f32x4 g0 = acc[ai][0][m][0] * sc, g1 = acc[ai][0][m][1] * sc, u0 = acc[ai][1][m][0] * sc, u1 = acc[ai][1][m][1] * sc;
;                 u32x4 w; w.x = cvt_pk_bf16(silu_mul(g0[0], u0[0]), silu_mul(g0[1], u0[1])); w.y = cvt_pk_bf16(silu_mul(g0[2], u0[2]), silu_mul(g0[3], u0[3]));
;                 w.z = cvt_pk_bf16(silu_mul(g1[0], u1[0]), silu_mul(g1[1], u1[1])); w.w = cvt_pk_bf16(silu_mul(g1[2], u1[2]), silu_mul(g1[3], u1[3]));
;                 __builtin_nontemporal_store(w, (u32x4*)(O + (size_t)row * ldc + col0)); }
	v_pk_fma_f32 v[106:107], v[106:107], v[178:179], v[178:179] op_sel_hi:[1,0,0]
	v_pk_fma_f32 v[108:109], v[108:109], v[178:179], v[178:179] op_sel_hi:[1,0,0]
	v_pk_fma_f32 v[110:111], v[110:111], v[178:179], v[178:179] op_sel_hi:[1,0,0]
	v_rcp_f32_e32 v104, v104
	v_rcp_f32_e32 v105, v105
	v_rcp_f32_e32 v106, v106
	v_rcp_f32_e32 v107, v107
	v_rcp_f32_e32 v108, v108
	v_rcp_f32_e32 v109, v109
	v_rcp_f32_e32 v110, v110
	v_rcp_f32_e32 v111, v111
	v_pk_mul_f32 v[96:97], v[96:97], v[104:105]
	v_pk_mul_f32 v[98:99], v[98:99], v[106:107]
	v_pk_mul_f32 v[100:101], v[100:101], v[108:109]
	v_pk_mul_f32 v[102:103], v[102:103], v[110:111]
	v_cvt_pk_bf16_f32 v104, v100, v101
	v_cvt_pk_bf16_f32 v105, v102, v103
	v_cvt_pk_bf16_f32 v106, v96, v97
	v_cvt_pk_bf16_f32 v107, v98, v99
	global_store_dwordx4 v[166:167], v[104:107], off nt
	v_lshl_add_u64 v[164:165], v[166:167], 0, s[98:99]
	v_pk_mul_f32 v[80:81], v[88:89], v[80:81]
	v_pk_mul_f32 v[82:83], v[90:91], v[82:83]
	v_pk_mul_f32 v[84:85], v[92:93], v[84:85]
	v_pk_mul_f32 v[86:87], v[94:95], v[86:87]
	v_pk_mul_f32 v[88:89], v[88:89], v[180:181] op_sel_hi:[1,0]
	v_pk_mul_f32 v[90:91], v[90:91], v[180:181] op_sel_hi:[1,0]
	v_pk_mul_f32 v[92:93], v[92:93], v[180:181] op_sel_hi:[1,0]
	v_pk_mul_f32 v[94:95], v[94:95], v[180:181] op_sel_hi:[1,0]
	v_exp_f32_e32 v88, v88
	v_exp_f32_e32 v89, v89
	v_exp_f32_e32 v90, v90
	v_exp_f32_e32 v91, v91
	v_exp_f32_e32 v92, v92
	v_exp_f32_e32 v93, v93
	v_exp_f32_e32 v94, v94
	v_exp_f32_e32 v95, v95
	v_pk_fma_f32 v[88:89], v[88:89], v[182:183], v[182:183] op_sel_hi:[1,0,0]
	v_pk_fma_f32 v[90:91], v[90:91], v[182:183], v[182:183] op_sel_hi:[1,0,0]
	v_pk_fma_f32 v[92:93], v[92:93], v[182:183], v[182:183] op_sel_hi:[1,0,0]
	v_pk_fma_f32 v[94:95], v[94:95], v[182:183], v[182:183] op_sel_hi:[1,0,0]
	v_rcp_f32_e32 v88, v88
	v_rcp_f32_e32 v89, v89
	v_rcp_f32_e32 v90, v90
	v_rcp_f32_e32 v91, v91
	v_rcp_f32_e32 v92, v92
	v_rcp_f32_e32 v93, v93
	v_rcp_f32_e32 v94, v94
	v_rcp_f32_e32 v95, v95
	v_pk_mul_f32 v[80:81], v[80:81], v[88:89]
	v_pk_mul_f32 v[82:83], v[82:83], v[90:91]
	v_pk_mul_f32 v[84:85], v[84:85], v[92:93]
	v_pk_mul_f32 v[86:87], v[86:87], v[94:95]
	v_cvt_pk_bf16_f32 v88, v84, v85
	v_cvt_pk_bf16_f32 v89, v86, v87
	v_cvt_pk_bf16_f32 v90, v80, v81
	v_cvt_pk_bf16_f32 v91, v82, v83
	global_store_dwordx4 v[164:165], v[88:91], off nt
	v_lshl_add_u64 v[166:167], v[164:165], 0, s[98:99]
	v_pk_mul_f32 v[64:65], v[72:73], v[64:65]
	v_pk_mul_f32 v[66:67], v[74:75], v[66:67]
	v_pk_mul_f32 v[68:69], v[76:77], v[68:69]
	v_pk_mul_f32 v[70:71], v[78:79], v[70:71]
	v_pk_mul_f32 v[72:73], v[72:73], v[184:185] op_sel_hi:[1,0]
	v_pk_mul_f32 v[74:75], v[74:75], v[184:185] op_sel_hi:[1,0]
	v_pk_mul_f32 v[76:77], v[76:77], v[184:185] op_sel_hi:[1,0]
	v_pk_mul_f32 v[78:79], v[78:79], v[184:185] op_sel_hi:[1,0]
	v_exp_f32_e32 v72, v72
	v_exp_f32_e32 v73, v73
	v_exp_f32_e32 v74, v74
	v_exp_f32_e32 v75, v75
	v_exp_f32_e32 v76, v76
	v_exp_f32_e32 v77, v77
	v_exp_f32_e32 v78, v78
	v_exp_f32_e32 v79, v79
	v_pk_fma_f32 v[72:73], v[72:73], v[186:187], v[186:187] op_sel_hi:[1,0,0]
	v_pk_fma_f32 v[74:75], v[74:75], v[186:187], v[186:187] op_sel_hi:[1,0,0]
	v_pk_fma_f32 v[76:77], v[76:77], v[186:187], v[186:187] op_sel_hi:[1,0,0]
	v_pk_fma_f32 v[78:79], v[78:79], v[186:187], v[186:187] op_sel_hi:[1,0,0]
	v_rcp_f32_e32 v72, v72
	v_rcp_f32_e32 v73, v73
	v_rcp_f32_e32 v74, v74
	v_rcp_f32_e32 v75, v75
	v_rcp_f32_e32 v76, v76
	v_rcp_f32_e32 v77, v77
	v_rcp_f32_e32 v78, v78
	v_rcp_f32_e32 v79, v79
	v_pk_mul_f32 v[64:65], v[64:65], v[72:73]
	v_pk_mul_f32 v[66:67], v[66:67], v[74:75]
	v_pk_mul_f32 v[68:69], v[68:69], v[76:77]
	v_pk_mul_f32 v[70:71], v[70:71], v[78:79]
	v_cvt_pk_bf16_f32 v72, v68, v69
	v_cvt_pk_bf16_f32 v73, v70, v71
	v_cvt_pk_bf16_f32 v74, v64, v65
	v_cvt_pk_bf16_f32 v75, v66, v67
	global_store_dwordx4 v[166:167], v[72:75], off nt
	s_mov_b32 s98, 0x6e000
	v_lshl_add_u64 v[164:165], v[166:167], 0, s[98:99]
	s_mov_b32 s98, 0x16000
	v_pk_mul_f32 v[48:49], v[56:57], v[48:49]
	v_pk_mul_f32 v[50:51], v[58:59], v[50:51]
	v_pk_mul_f32 v[52:53], v[60:61], v[52:53]
	v_pk_mul_f32 v[54:55], v[62:63], v[54:55]
	v_pk_mul_f32 v[56:57], v[56:57], v[188:189] op_sel_hi:[1,0]
	v_pk_mul_f32 v[58:59], v[58:59], v[188:189] op_sel_hi:[1,0]
	v_pk_mul_f32 v[60:61], v[60:61], v[188:189] op_sel_hi:[1,0]
	v_pk_mul_f32 v[62:63], v[62:63], v[188:189] op_sel_hi:[1,0]
	v_exp_f32_e32 v56, v56
	v_exp_f32_e32 v57, v57
	v_exp_f32_e32 v58, v58
	v_exp_f32_e32 v59, v59
	v_exp_f32_e32 v60, v60
	v_exp_f32_e32 v61, v61
	v_exp_f32_e32 v62, v62
	v_exp_f32_e32 v63, v63
	v_pk_fma_f32 v[56:57], v[56:57], v[190:191], v[190:191] op_sel_hi:[1,0,0]
	v_pk_fma_f32 v[58:59], v[58:59], v[190:191], v[190:191] op_sel_hi:[1,0,0]
	v_pk_fma_f32 v[60:61], v[60:61], v[190:191], v[190:191] op_sel_hi:[1,0,0]
	v_pk_fma_f32 v[62:63], v[62:63], v[190:191], v[190:191] op_sel_hi:[1,0,0]
	v_rcp_f32_e32 v56, v56
	v_rcp_f32_e32 v57, v57
	v_rcp_f32_e32 v58, v58
	v_rcp_f32_e32 v59, v59
	v_rcp_f32_e32 v60, v60
	v_rcp_f32_e32 v61, v61
; __device__ __forceinline__ unsigned cvt_pk_bf16(float lo, float hi) { const cvt_f32x2_t v = {lo, hi}; const cvt_bf16x2_t b = __builtin_convertvector(v, cvt_bf16x2_t); return __builtin_bit_cast(unsigned, b); }
; __device__ __forceinline__ float silu_mul(float g, float u) { return g * u * __builtin_amdgcn_rcpf(1.0f + __builtin_amdgcn_exp2f(g * -1.4426950408889634f)); }
;     __device__ __forceinline__ void operator()(const f32x4 (&acc)[2][2][4][2], const Unit& u, int wr, int wc, int fr, int fq) const {
;     ...
;             for (int m = 0; m < 4; ++m) { const int row = row0 + ai * HALF + m * 16;
;                 const float sc = rstd_from_slots(slots, row, fq);
;                 const f32x4 g0 = acc[ai][0][m][0] * sc, g1 = acc[ai][0][m][1] * sc, u0 = acc[ai][1][m][0] * sc, u1 = acc[ai][1][m][1] * sc;
;                 u32x4 w; w.x = cvt_pk_bf16(silu_mul(g0[0], u0[0]), silu_mul(g0[1], u0[1])); w.y = cvt_pk_bf16(silu_mul(g0[2], u0[2]), silu_mul(g0[3], u0[3]));
;                 w.z = cvt_pk_bf16(silu_mul(g1[0], u1[0]), silu_mul(g1[1], u1[1])); w.w = cvt_pk_bf16(silu_mul(g1[2], u1[2]), silu_mul(g1[3], u1[3]));
;                 __builtin_nontemporal_store(w, (u32x4*)(O + (size_t)row * ldc + col0)); }
	v_rcp_f32_e32 v62, v62
	v_rcp_f32_e32 v63, v63
	v_pk_mul_f32 v[48:49], v[48:49], v[56:57]
	v_pk_mul_f32 v[50:51], v[50:51], v[58:59]
	v_pk_mul_f32 v[52:53], v[52:53], v[60:61]
	v_pk_mul_f32 v[54:55], v[54:55], v[62:63]
	v_cvt_pk_bf16_f32 v56, v52, v53
	v_cvt_pk_bf16_f32 v57, v54, v55
	v_cvt_pk_bf16_f32 v58, v48, v49
	v_cvt_pk_bf16_f32 v59, v50, v51
	global_store_dwordx4 v[164:165], v[56:59], off nt
	v_lshl_add_u64 v[166:167], v[164:165], 0, s[98:99]
	v_pk_mul_f32 v[32:33], v[40:41], v[32:33]
	v_pk_mul_f32 v[34:35], v[42:43], v[34:35]
	v_pk_mul_f32 v[36:37], v[44:45], v[36:37]
	v_pk_mul_f32 v[38:39], v[46:47], v[38:39]
	v_pk_mul_f32 v[40:41], v[40:41], v[192:193] op_sel_hi:[1,0]
	v_pk_mul_f32 v[42:43], v[42:43], v[192:193] op_sel_hi:[1,0]
	v_pk_mul_f32 v[44:45], v[44:45], v[192:193] op_sel_hi:[1,0]
	v_pk_mul_f32 v[46:47], v[46:47], v[192:193] op_sel_hi:[1,0]
	v_exp_f32_e32 v40, v40
	v_exp_f32_e32 v41, v41
	v_exp_f32_e32 v42, v42
	v_exp_f32_e32 v43, v43
	v_exp_f32_e32 v44, v44
	v_exp_f32_e32 v45, v45
	v_exp_f32_e32 v46, v46
	v_exp_f32_e32 v47, v47
	v_pk_fma_f32 v[40:41], v[40:41], v[194:195], v[194:195] op_sel_hi:[1,0,0]
	v_pk_fma_f32 v[42:43], v[42:43], v[194:195], v[194:195] op_sel_hi:[1,0,0]
	v_pk_fma_f32 v[44:45], v[44:45], v[194:195], v[194:195] op_sel_hi:[1,0,0]
	v_pk_fma_f32 v[46:47], v[46:47], v[194:195], v[194:195] op_sel_hi:[1,0,0]
	v_rcp_f32_e32 v40, v40
	v_rcp_f32_e32 v41, v41
	v_rcp_f32_e32 v42, v42
	v_rcp_f32_e32 v43, v43
	v_rcp_f32_e32 v44, v44
	v_rcp_f32_e32 v45, v45
	v_rcp_f32_e32 v46, v46
	v_rcp_f32_e32 v47, v47
	v_pk_mul_f32 v[32:33], v[32:33], v[40:41]
	v_pk_mul_f32 v[34:35], v[34:35], v[42:43]
	v_pk_mul_f32 v[36:37], v[36:37], v[44:45]
	v_pk_mul_f32 v[38:39], v[38:39], v[46:47]
	v_cvt_pk_bf16_f32 v40, v36, v37
	v_cvt_pk_bf16_f32 v41, v38, v39
	v_cvt_pk_bf16_f32 v42, v32, v33
	v_cvt_pk_bf16_f32 v43, v34, v35
	global_store_dwordx4 v[166:167], v[40:43], off nt
	v_lshl_add_u64 v[164:165], v[166:167], 0, s[98:99]
	v_pk_mul_f32 v[16:17], v[24:25], v[16:17]
	v_pk_mul_f32 v[18:19], v[26:27], v[18:19]
	v_pk_mul_f32 v[20:21], v[28:29], v[20:21]
	v_pk_mul_f32 v[22:23], v[30:31], v[22:23]
	v_pk_mul_f32 v[24:25], v[24:25], v[196:197] op_sel_hi:[1,0]
	v_pk_mul_f32 v[26:27], v[26:27], v[196:197] op_sel_hi:[1,0]
	v_pk_mul_f32 v[28:29], v[28:29], v[196:197] op_sel_hi:[1,0]
	v_pk_mul_f32 v[30:31], v[30:31], v[196:197] op_sel_hi:[1,0]
	v_exp_f32_e32 v24, v24
	v_exp_f32_e32 v25, v25
	v_exp_f32_e32 v26, v26
	v_exp_f32_e32 v27, v27
	v_exp_f32_e32 v28, v28
	v_exp_f32_e32 v29, v29
	v_exp_f32_e32 v30, v30
	v_exp_f32_e32 v31, v31
	v_pk_fma_f32 v[24:25], v[24:25], v[198:199], v[198:199] op_sel_hi:[1,0,0]
	v_pk_fma_f32 v[26:27], v[26:27], v[198:199], v[198:199] op_sel_hi:[1,0,0]
	v_pk_fma_f32 v[28:29], v[28:29], v[198:199], v[198:199] op_sel_hi:[1,0,0]
	v_pk_fma_f32 v[30:31], v[30:31], v[198:199], v[198:199] op_sel_hi:[1,0,0]
	v_rcp_f32_e32 v24, v24
	v_rcp_f32_e32 v25, v25
	v_rcp_f32_e32 v26, v26
	v_rcp_f32_e32 v27, v27
	v_rcp_f32_e32 v28, v28
	v_rcp_f32_e32 v29, v29
	v_rcp_f32_e32 v30, v30
	v_rcp_f32_e32 v31, v31
	v_pk_mul_f32 v[16:17], v[16:17], v[24:25]
	v_pk_mul_f32 v[18:19], v[18:19], v[26:27]
	v_pk_mul_f32 v[20:21], v[20:21], v[28:29]
	v_pk_mul_f32 v[22:23], v[22:23], v[30:31]
	v_cvt_pk_bf16_f32 v24, v20, v21
	v_cvt_pk_bf16_f32 v25, v22, v23
	v_cvt_pk_bf16_f32 v26, v16, v17
	v_cvt_pk_bf16_f32 v27, v18, v19
	global_store_dwordx4 v[164:165], v[24:27], off nt
	v_lshl_add_u64 v[166:167], v[164:165], 0, s[98:99]
	v_pk_mul_f32 v[0:1], v[8:9], v[0:1]
	v_pk_mul_f32 v[2:3], v[10:11], v[2:3]
	v_pk_mul_f32 v[4:5], v[12:13], v[4:5]
	v_pk_mul_f32 v[6:7], v[14:15], v[6:7]
	v_pk_mul_f32 v[8:9], v[8:9], v[200:201] op_sel_hi:[1,0]
	v_pk_mul_f32 v[10:11], v[10:11], v[200:201] op_sel_hi:[1,0]
	v_pk_mul_f32 v[12:13], v[12:13], v[200:201] op_sel_hi:[1,0]
	v_pk_mul_f32 v[14:15], v[14:15], v[200:201] op_sel_hi:[1,0]
	v_exp_f32_e32 v8, v8
	v_exp_f32_e32 v9, v9
	v_exp_f32_e32 v10, v10
	v_exp_f32_e32 v11, v11
	v_exp_f32_e32 v12, v12
	v_exp_f32_e32 v13, v13
	v_exp_f32_e32 v14, v14
	v_exp_f32_e32 v15, v15
	v_pk_fma_f32 v[8:9], v[8:9], v[202:203], v[202:203] op_sel_hi:[1,0,0]
	v_pk_fma_f32 v[10:11], v[10:11], v[202:203], v[202:203] op_sel_hi:[1,0,0]
	v_pk_fma_f32 v[12:13], v[12:13], v[202:203], v[202:203] op_sel_hi:[1,0,0]
	v_pk_fma_f32 v[14:15], v[14:15], v[202:203], v[202:203] op_sel_hi:[1,0,0]
	v_rcp_f32_e32 v8, v8
	v_rcp_f32_e32 v9, v9
	v_rcp_f32_e32 v10, v10
	v_rcp_f32_e32 v11, v11
	v_rcp_f32_e32 v12, v12
	v_rcp_f32_e32 v13, v13
	v_rcp_f32_e32 v14, v14
	v_rcp_f32_e32 v15, v15
	v_pk_mul_f32 v[0:1], v[0:1], v[8:9]
	v_pk_mul_f32 v[2:3], v[2:3], v[10:11]
	v_pk_mul_f32 v[4:5], v[4:5], v[12:13]
	v_pk_mul_f32 v[6:7], v[6:7], v[14:15]
	v_cvt_pk_bf16_f32 v8, v4, v5
	v_cvt_pk_bf16_f32 v9, v6, v7
	v_cvt_pk_bf16_f32 v10, v0, v1
	v_cvt_pk_bf16_f32 v11, v2, v3
	global_store_dwordx4 v[166:167], v[8:11], off nt
	s_cbranch_vccnz .LBB0_1107
	s_andn2_b64 vcc, exec, s[6:7]
	s_cbranch_vccnz .LBB0_1106
	s_barrier
	s_branch .LBB0_1106
